# baseline (speedup 1.0000x reference)
; template <int DK> ...
;     ...
;   __syncthreads();
; }
; __device__ void scan_phase(const Ctx& p) {
;   char* ws = p.ws;
;   const u16* h0 = (const u16*)(ws + OFF_H0);
;   const float* gem = (const float*)(ws + OFF_DV); const float* gelm = gem + 256 * 1024;
;   const float* hem = gelm + 256 * 1024; const float* helm = hem + 256 * 2048;
;   for (int item = blockIdx.x; item < 256; item += gridDim.x) {
.LBB0_224:
	s_setprio 0
	s_barrier

; __device__ __forceinline__ int ltid() { int t = threadIdx.x; asm volatile("" : "+v"(t)); return t; }
; template <int DK> ...
;     ...
;   const int tid = ltid(), w = tid >> 6, lane = tid & 63, fr = lane & 15, fq = lane >> 4;
;   f32x4 S[NA][2];
; #pragma unroll
;   for (int a = 0; a < NA; ++a) { S[a][0] = (f32x4){0.f, 0.f, 0.f, 0.f}; S[a][1] = (f32x4){0.f, 0.f, 0.f, 0.f}; }
;   uint4 rq0, rq1, rq2, rq3, rk0, rk1, rk2, rk3, rt0, rt1, rt2, rt3, rv;
;   float4 e4n0, e4n1, l4n0, l4n1;
;   rv = make_uint4(0, 0, 0, 0);
;   rq2 = rq3 = rk2 = rk3 = rt2 = rt3 = rv;
;   e4n1 = l4n1 = make_float4(0.f, 0.f, 0.f, 0.f);
;     ...
;   auto scan_load = [&](const int c_) {
;     const long row_ = (long)c_ * 64;
;     SL1(0, rq0, rk0, rt0) SL1(1, rq1, rk1, rt1) SL1(2, rq2, rk2, rt2) SL1(3, rq3, rk3, rt3)
;     if (tid < 256) rv = *(const uint4*)(vg + (row_ + (tid >> 2)) * H0LD + (tid & 3) * 8);
;     {
;       const int d0_ = (w * NA + 0) * 16 + fq * 4;
;       e4n0 = *(const float4*)(em + (long)(ck0 + c_) * CH + d0_);
;       l4n0 = *(const float4*)(elm + (long)(ck0 + c_) * CH + d0_);
;     }
;     if (NA > 1) {
;       const int d0_ = (w * NA + 1) * 16 + fq * 4;
;       e4n1 = *(const float4*)(em + (long)(ck0 + c_) * CH + d0_);
;       l4n1 = *(const float4*)(elm + (long)(ck0 + c_) * CH + d0_);
;     }
;   };
;   scan_load(0);
.LBB0_231:
	s_or_b64 exec, exec, s[6:7]
	s_lshl_b32 s8, s10, 2
	s_add_u32 s6, s27, s8
	s_addc_u32 s7, s60, 0
	s_add_u32 s8, s84, s8
	s_addc_u32 s9, s87, 0
	s_lshl_b64 s[38:39], s[52:53], 25
	v_ashrrev_i32_e32 v53, 6, v42
	v_bfe_u32 v59, v42, 4, 2
	s_lshl_b64 s[10:11], s[34:35], 13
	v_lshlrev_b32_e32 v60, 4, v53
	v_lshlrev_b32_e32 v61, 2, v59
	s_add_u32 s12, s6, s10
	v_or_b32_e32 v54, v61, v60
	s_addc_u32 s13, s7, s11
	v_ashrrev_i32_e32 v55, 31, v54
	s_add_u32 s10, s8, s10
	v_lshlrev_b64 v[56:57], 2, v[54:55]
	s_addc_u32 s11, s9, s11
	v_lshl_add_u64 v[30:31], s[12:13], 0, v[56:57]
	v_lshl_add_u64 v[32:33], s[10:11], 0, v[56:57]
	s_waitcnt vmcnt(0)
	global_load_dwordx4 v[34:37], v[30:31], off
	s_nop 0
	global_load_dwordx4 v[30:33], v[32:33], off
	v_lshl_add_u64 v[70:71], s[6:7], 0, v[56:57]
	s_movk_i32 s6, 0x110
	s_lshl_b32 s35, s42, 6
	v_lshlrev_b32_e32 v0, 1, v38
	v_lshl_add_u64 v[72:73], s[8:9], 0, v[56:57]
	v_mul_lo_u32 v56, v50, s6
	s_add_i32 s34, s34, 1
	s_and_b32 s35, s35, 0xc0
	v_add3_u32 v0, 16, v0, v56
	v_lshrrev_b32_e32 v56, 3, v42
	s_movk_i32 s8, 0x90
	v_lshlrev_b32_e32 v45, 1, v45
	v_lshrrev_b32_e32 v44, 3, v44
	s_add_u32 s56, s35, s30
	v_mul_lo_u32 v56, v56, s8
	v_and_b32_e32 v45, 0x70, v45
	v_mul_lo_u32 v44, v44, s8
	s_addc_u32 s57, 0, s31
	v_add3_u32 v92, 16, v56, v45
	v_add3_u32 v94, 16, v44, v45
	v_mul_u32_u24_e32 v44, 0x90, v52
	v_lshlrev_b32_e32 v45, 1, v51
	v_ashrrev_i32_e32 v52, 7, v42
	v_lshl_add_u64 v[46:47], s[56:57], 0, v[46:47]
	v_and_b32_e32 v58, 15, v42
	v_add3_u32 v95, 16, v44, v45
	v_readlane_b32 s7, v252, 35
	v_lshlrev_b32_e32 v44, 4, v52
	v_lshl_add_u64 v[46:47], v[48:49], 1, v[46:47]
	v_lshl_add_u32 v51, v54, 1, s7
	v_or_b32_e32 v54, v44, v58
	v_lshl_add_u64 v[76:77], s[66:67], 0, v[46:47]
	v_mov_b64_e32 v[46:47], s[30:31]
	v_lshlrev_b32_e32 v55, 1, v40
	v_mul_lo_u32 v56, v43, s6
	v_mov_b32_e32 v45, s7
	v_mul_lo_u32 v42, v54, s6
	v_and_or_b32 v57, v60, 16, v58
	v_mad_i64_i32 v[48:49], s[30:31], v43, s51, v[46:47]
	v_add3_u32 v93, 16, v55, v56
	v_add_u32_e32 v96, 16, v42
	v_or_b32_e32 v56, v61, v44
	v_mad_u32_u24 v61, v57, s6, v45
	v_lshlrev_b32_e32 v45, 7, v54
	v_lshl_add_u64 v[40:41], v[40:41], 1, v[48:49]
	v_lshlrev_b32_e32 v97, 4, v59
	v_sub_u32_e32 v45, v96, v45
	v_lshl_add_u64 v[78:79], s[66:67], 0, v[40:41]
	v_mad_i64_i32 v[40:41], s[30:31], v50, s51, v[46:47]
	v_add_u32_e32 v98, v45, v97
	v_ashrrev_i32_e32 v45, 31, v44
	v_lshl_add_u64 v[38:39], v[38:39], 1, v[40:41]
	v_lshlrev_b32_e32 v42, 1, v53
	v_lshl_add_u64 v[80:81], s[66:67], 0, v[38:39]
	v_lshl_or_b32 v38, v59, 14, s38
	v_mov_b32_e32 v39, s39
	v_lshlrev_b64 v[40:41], 12, v[44:45]
	v_and_b32_e32 v55, 2, v42
	v_add_u32_e32 v42, 16, v97
	v_or_b32_e32 v54, v60, v58
	v_lshl_add_u64 v[38:39], v[38:39], 0, v[40:41]
	v_lshlrev_b32_e32 v40, 5, v53
	v_mad_u32_u24 v99, v57, s8, v42
	v_mad_u64_u32 v[74:75], s[6:7], v54, s8, v[42:43]
	v_lshl_or_b32 v57, v55, 4, v58
	v_or_b32_e32 v38, s35, v38
	v_and_b32_e32 v40, 32, v40
	v_lshlrev_b32_e32 v41, 1, v58
	v_mul_u32_u24_e32 v54, 0x110, v58
	v_cmp_le_i32_e64 s[6:7], v55, v52
	v_mul_u32_u24_e32 v60, 0x110, v57
	v_mul_lo_u32 v62, v56, s8
	v_or_b32_e32 v63, 1, v56
	v_or_b32_e32 v64, 2, v56
	v_or_b32_e32 v65, 3, v56
	v_cmp_ge_i32_e64 s[8:9], v55, v52
	v_or_b32_e32 v52, 16, v57
	v_mul_u32_u24_e32 v55, 0x90, v58
	v_lshl_add_u32 v85, v57, 1, 16
	v_or3_b32 v38, v38, v40, v41
	v_mov_b32_e32 v84, 0
	v_cmp_gt_i32_e64 s[10:11], v57, v56
	v_cmp_gt_i32_e64 s[12:13], v57, v63
	v_cmp_gt_i32_e64 s[14:15], v57, v64
	v_cmp_gt_i32_e64 s[16:17], v57, v65
	v_cmp_gt_i32_e64 s[18:19], v52, v56
	v_cmp_gt_i32_e64 s[20:21], v52, v63
	v_cmp_gt_i32_e64 s[22:23], v52, v64
	v_cmp_gt_i32_e64 s[24:25], v52, v65
	s_mov_b32 s29, s53
	v_lshl_add_u64 v[82:83], s[66:67], 0, v[38:39]
	s_mov_b32 s35, 0
	v_add_u32_e32 v75, v51, v54
	v_add_u32_e32 v100, v61, v97
	v_add_u32_e32 v101, v42, v55
	v_add_u32_e32 v102, v42, v60
	v_add_u32_e32 v103, v85, v62
	v_mov_b32_e32 v85, v84
	v_mov_b32_e32 v86, v84
	v_mov_b32_e32 v87, v84
	v_mov_b32_e32 v88, v84
	v_mov_b32_e32 v89, v84
	v_mov_b32_e32 v90, v84
	v_mov_b32_e32 v91, v84
	v_readfirstlane_b32 s98, v139
	s_lshr_b32 s98, s98, 6
	s_cmp_lt_u32 s98, 4
	s_cbranch_scc1 .Lscan_noprio_h
	s_setprio 1
; __device__ __forceinline__ u16 f2bf(float f) { return (u16)(pack2(f, 0.f) & 0xffffu); }
; #define RAWSYNC do { asm volatile("s_waitcnt lgkmcnt(0)" ::: "memory"); __builtin_amdgcn_s_barrier(); asm volatile("" ::: "memory"); } while (0)
; template <int DK> ...
;     ...
;         if (tj <= ti) {
; #pragma unroll
;           for (int ks = 0; ks < DK / 32; ++ks) {
;             bf16x8 fb = *(const bf16x8*)(Kt + (tj * 16 + fr) * PQ + ks * 32 + fq * 8);
;             a = __builtin_amdgcn_mfma_f32_16x16x32_bf16(qf[ks], fb, a, 0, 0, 0);
;           }
;         }
; #pragma unroll
;         for (int r = 0; r < 4; ++r) {
;           int i = ti * 16 + fq * 4 + r, j = tj * 16 + fr;
;           Pm[i * 72 + j] = f2bf(j <= i ? a[r] : 0.f);
;         }
;       }
;     }
;     RAWSYNC;
;     {
;       const int ti = w >> 1, tv = w & 1;
;       f32x4 a = {0.f, 0.f, 0.f, 0.f};
; #pragma unroll
;       for (int ks = 0; ks < DK / 32; ++ks) {
;         bf16x8 fb = *(const bf16x8*)(ST + (tv * 16 + fr) * PQ + ks * 32 + fq * 8);
;         a = __builtin_amdgcn_mfma_f32_16x16x32_bf16(qf[ks], fb, a, 0, 0, 0);
;       }
; #pragma unroll
;       for (int ks = 0; ks < 2; ++ks) {
;         bf16x8 fa = *(const bf16x8*)(Pm + (ti * 16 + fr) * 72 + ks * 32 + fq * 8);
;         bf16x8 fb = *(const bf16x8*)(VT + (tv * 16 + fr) * 72 + ks * 32 + fq * 8);
;         a = __builtin_amdgcn_mfma_f32_16x16x32_bf16(fa, fb, a, 0, 0, 0);
;       }
; #pragma unroll
;       for (int r = 0; r < 4; ++r) og[(row + ti * 16 + fq * 4 + r) * 2048 + tv * 16 + fr] = f2bf(a[r]);
;     }
; #pragma unroll
;     for (int a = 0; a < NA; ++a) {
;       const int dt = w * NA + a;
; #pragma unroll
;       for (int tv = 0; tv < 2; ++tv) {
;         f32x4 u = {0.f, 0.f, 0.f, 0.f};
; #pragma unroll
;         for (int ks = 0; ks < 2; ++ks) {
;           bf16x8 fa = *(const bf16x8*)(KtT + (dt * 16 + fr) * 72 + ks * 32 + fq * 8);
;           bf16x8 fb = *(const bf16x8*)(VT + (tv * 16 + fr) * 72 + ks * 32 + fq * 8);
;           u = __builtin_amdgcn_mfma_f32_16x16x32_bf16(fa, fb, u, 0, 0, 0);
;         }
;         S[a][tv][0] = e4[a].x * l4[a].x * S[a][tv][0] + l4[a].x * u[0];
;         S[a][tv][1] = e4[a].y * l4[a].y * S[a][tv][1] + l4[a].y * u[1];
;         S[a][tv][2] = e4[a].z * l4[a].z * S[a][tv][2] + l4[a].z * u[2];
;         S[a][tv][3] = e4[a].w * l4[a].w * S[a][tv][3] + l4[a].w * u[3];
;       }
;     }
.Lscan_noprio_h:
	s_branch .LBB0_233
.LBB0_232:
	s_or_b64 exec, exec, s[30:31]
	s_nop 5
	v_cvt_pk_bf16_f32 v62, v62, s0
	v_cndmask_b32_e64 v62, v62, 0, s[18:19]
	ds_write_b16 v103, v62 offset:57888
	v_cvt_pk_bf16_f32 v62, v63, s0
	v_cndmask_b32_e64 v62, v62, 0, s[20:21]
	ds_write_b16 v103, v62 offset:58032
	v_cvt_pk_bf16_f32 v62, v64, s0
	v_cndmask_b32_e64 v62, v62, 0, s[22:23]
	ds_write_b16 v103, v62 offset:58176
	v_cvt_pk_bf16_f32 v62, v65, s0
	v_cndmask_b32_e64 v62, v62, 0, s[24:25]
	ds_write_b16 v103, v62 offset:58320
	s_waitcnt lgkmcnt(0)
	s_barrier
	ds_read_b128 v[216:219], v100
	ds_read_b128 v[220:223], v100 offset:64
	ds_read_b128 v[224:227], v100 offset:128
	ds_read_b128 v[228:231], v100 offset:192
	ds_read_b128 v[232:235], v98 offset:57856
	ds_read_b128 v[236:239], v99 offset:53248
	ds_read_b128 v[240:243], v98 offset:57920
	ds_read_b128 v[244:247], v99 offset:53312
	s_brev_b32 s30, 32
	s_add_i32 s35, s35, 1
	v_lshl_add_u64 v[76:77], v[76:77], 0, s[70:71]
	v_lshl_add_u64 v[78:79], v[78:79], 0, s[70:71]
	v_lshl_add_u64 v[80:81], v[80:81], 0, s[70:71]
	s_cmpk_lg_i32 s35, 0x80
	s_waitcnt lgkmcnt(7)
	v_mfma_f32_16x16x32_bf16 v[58:61], v[58:61], v[216:219], 0
	s_waitcnt lgkmcnt(6)
	v_mfma_f32_16x16x32_bf16 v[54:57], v[54:57], v[220:223], v[58:61]
	s_waitcnt lgkmcnt(5)
	v_mfma_f32_16x16x32_bf16 v[50:53], v[50:53], v[224:227], v[54:57]
	s_waitcnt lgkmcnt(4)
	v_mfma_f32_16x16x32_bf16 v[46:49], v[46:49], v[228:231], v[50:53]
	v_pk_mul_f32 v[58:59], v[30:31], v[34:35]
	v_pk_mul_f32 v[60:61], v[32:33], v[36:37]
	s_waitcnt lgkmcnt(2)
	v_mfma_f32_16x16x32_bf16 v[46:49], v[232:235], v[236:239], v[46:49]
	s_waitcnt lgkmcnt(0)
	v_mfma_f32_16x16x32_bf16 v[46:49], v[240:243], v[244:247], v[46:49]
	v_lshl_add_u64 v[50:51], v[82:83], 0, s[28:29]
	v_add_co_u32_e32 v52, vcc, s30, v50
	s_mov_b32 s30, 0x4001000
	s_nop 4
	v_cvt_pk_bf16_f32 v46, v46, s0
	v_addc_co_u32_e32 v53, vcc, 0, v51, vcc
	global_store_short v[52:53], v46, off
	v_add_co_u32_e32 v46, vcc, s30, v50
	v_cvt_pk_bf16_f32 v52, v47, s0
	s_nop 0
	v_addc_co_u32_e32 v47, vcc, 0, v51, vcc
	s_mov_b32 s30, 0x4002000
	global_store_short v[46:47], v52, off
	v_add_co_u32_e32 v46, vcc, s30, v50
	v_cvt_pk_bf16_f32 v48, v48, s0
	s_nop 0
	v_addc_co_u32_e32 v47, vcc, 0, v51, vcc
	s_mov_b32 s30, 0x4003000
	global_store_short v[46:47], v48, off
	v_add_co_u32_e32 v46, vcc, s30, v50
	v_cvt_pk_bf16_f32 v48, v49, s0
	s_nop 0
	v_addc_co_u32_e32 v47, vcc, 0, v51, vcc
	global_store_short v[46:47], v48, off
	ds_read_b128 v[216:219], v74 offset:34816
	ds_read_b128 v[224:227], v101 offset:53248
	ds_read_b128 v[220:223], v74 offset:34880
	ds_read_b128 v[228:231], v101 offset:53312
	ds_read_b128 v[232:235], v101 offset:55552
	ds_read_b128 v[236:239], v101 offset:55616
	s_mov_b64 s[30:31], 0x40000
	v_lshl_add_u64 v[82:83], v[82:83], 0, s[30:31]
	s_waitcnt lgkmcnt(4)
	v_mfma_f32_16x16x32_bf16 v[46:49], v[216:219], v[224:227], 0
	s_waitcnt lgkmcnt(2)
	v_mfma_f32_16x16x32_bf16 v[46:49], v[220:223], v[228:231], v[46:49]
	s_waitcnt lgkmcnt(1)
	v_mfma_f32_16x16x32_bf16 v[34:37], v[216:219], v[232:235], 0
	s_waitcnt lgkmcnt(0)
	v_mfma_f32_16x16x32_bf16 v[34:37], v[220:223], v[236:239], v[34:37]
	s_nop 7
	v_pk_mul_f32 v[48:49], v[32:33], v[48:49]
	v_pk_mul_f32 v[46:47], v[30:31], v[46:47]
	v_pk_fma_f32 v[86:87], v[86:87], v[60:61], v[48:49]
	v_pk_fma_f32 v[84:85], v[84:85], v[58:59], v[46:47]
	s_nop 7
	v_pk_mul_f32 v[32:33], v[32:33], v[36:37]
	v_pk_mul_f32 v[30:31], v[30:31], v[34:35]
	v_pk_fma_f32 v[90:91], v[90:91], v[60:61], v[32:33]
	v_pk_fma_f32 v[88:89], v[88:89], v[58:59], v[30:31]
	s_waitcnt vmcnt(0)
	v_mov_b64_e32 v[30:31], v[42:43]
	v_mov_b64_e32 v[34:35], v[38:39]
	v_mov_b64_e32 v[32:33], v[44:45]
	v_mov_b64_e32 v[36:37], v[40:41]
	s_cbranch_scc0 .LBB0_245

; template <int DK> ...
;     ...
;   __syncthreads();
; }
; __device__ void scan_phase(const Ctx& p) {
;   char* ws = p.ws;
;   const u16* h0 = (const u16*)(ws + OFF_H0);
;   const float* gem = (const float*)(ws + OFF_DV); const float* gelm = gem + 256 * 1024;
;   const float* hem = gelm + 256 * 1024; const float* helm = hem + 256 * 2048;
;   for (int item = blockIdx.x; item < 256; item += gridDim.x) {
.LBB0_245:
	s_setprio 0
	s_barrier
	s_branch .LBB0_225

; __device__ __forceinline__ int ltid() { int t = threadIdx.x; asm volatile("" : "+v"(t)); return t; }
; template <int DK> ...
;     ...
;   const int tid = ltid(), w = tid >> 6, lane = tid & 63, fr = lane & 15, fq = lane >> 4;
;   f32x4 S[NA][2];
; #pragma unroll
;   for (int a = 0; a < NA; ++a) { S[a][0] = (f32x4){0.f, 0.f, 0.f, 0.f}; S[a][1] = (f32x4){0.f, 0.f, 0.f, 0.f}; }
;   uint4 rq0, rq1, rq2, rq3, rk0, rk1, rk2, rk3, rt0, rt1, rt2, rt3, rv;
;   float4 e4n0, e4n1, l4n0, l4n1;
;   rv = make_uint4(0, 0, 0, 0);
;   rq2 = rq3 = rk2 = rk3 = rt2 = rt3 = rv;
;   e4n1 = l4n1 = make_float4(0.f, 0.f, 0.f, 0.f);
;     ...
;   auto scan_load = [&](const int c_) {
;     const long row_ = (long)c_ * 64;
;     SL1(0, rq0, rk0, rt0) SL1(1, rq1, rk1, rt1) SL1(2, rq2, rk2, rt2) SL1(3, rq3, rk3, rt3)
;     if (tid < 256) rv = *(const uint4*)(vg + (row_ + (tid >> 2)) * H0LD + (tid & 3) * 8);
;     {
;       const int d0_ = (w * NA + 0) * 16 + fq * 4;
;       e4n0 = *(const float4*)(em + (long)(ck0 + c_) * CH + d0_);
;       l4n0 = *(const float4*)(elm + (long)(ck0 + c_) * CH + d0_);
;     }
;     if (NA > 1) {
;       const int d0_ = (w * NA + 1) * 16 + fq * 4;
;       e4n1 = *(const float4*)(em + (long)(ck0 + c_) * CH + d0_);
;       l4n1 = *(const float4*)(elm + (long)(ck0 + c_) * CH + d0_);
;     }
;   };
;   scan_load(0);
.LBB0_250:
	s_or_b64 exec, exec, s[8:9]
	s_lshl_b32 s8, s13, 2
	v_readlane_b32 s9, v252, 57
	s_add_u32 s38, s9, s8
	v_readlane_b32 s9, v252, 58
	s_addc_u32 s39, s9, 0
	s_add_u32 s54, s85, s8
	s_addc_u32 s55, s26, 0
	s_lshl_b64 s[34:35], s[6:7], 25
	v_ashrrev_i32_e32 v0, 6, v76
	v_bfe_u32 v96, v76, 4, 2
	s_lshl_b64 s[6:7], s[28:29], 12
	v_lshlrev_b32_e32 v97, 5, v0
	v_lshlrev_b32_e32 v98, 2, v96
	s_add_u32 s8, s38, s6
	v_or_b32_e32 v54, v98, v97
	s_addc_u32 s9, s39, s7
	v_ashrrev_i32_e32 v55, 31, v54
	s_add_u32 s6, s54, s6
	v_lshlrev_b64 v[94:95], 2, v[54:55]
	s_addc_u32 s7, s55, s7
	v_lshl_add_u64 v[54:55], s[8:9], 0, v[94:95]
	v_lshl_add_u64 v[56:57], s[6:7], 0, v[94:95]
	global_load_dwordx4 v[66:69], v[54:55], off
	global_load_dwordx4 v[58:61], v[54:55], off offset:64
	global_load_dwordx4 v[62:65], v[56:57], off
	s_nop 0
	global_load_dwordx4 v[54:57], v[56:57], off offset:64
	s_movk_i32 s10, 0x90
	v_lshlrev_b32_e32 v91, 1, v91
	v_lshrrev_b32_e32 v80, 3, v80
	s_movk_i32 s7, 0x210
	s_add_i32 s6, 16, 0x10800
	v_and_b32_e32 v91, 0x70, v91
	v_mul_lo_u32 v80, v80, s10
	v_lshlrev_b32_e32 v101, 1, v74
	v_add3_u32 v169, s6, v80, v91
	v_mul_lo_u32 v80, v81, s7
	v_add3_u32 v170, 16, v101, v80
	v_lshrrev_b32_e32 v80, 3, v82
	v_mul_lo_u32 v80, v80, s10
	v_lshlrev_b32_e32 v102, 1, v78
	v_add3_u32 v171, s6, v80, v91
	v_mul_lo_u32 v80, v83, s7
	v_add3_u32 v172, 16, v102, v80
	v_lshrrev_b32_e32 v80, 3, v86
	v_mul_lo_u32 v80, v80, s10
	v_lshlrev_b32_e32 v99, 1, v70
	v_mul_lo_u32 v103, v90, s7
	v_add3_u32 v173, s6, v80, v91
	v_mul_u32_u24_e32 v80, 0x90, v92
	v_lshlrev_b32_e32 v82, 1, v87
	v_readlane_b32 s8, v252, 36
	v_lshl_add_u64 v[130:131], s[38:39], 0, v[94:95]
	s_add_i32 s38, s28, 1
	s_lshl_b32 s28, s57, 10
	v_and_b32_e32 v93, 15, v76
	v_add3_u32 v136, 16, v99, v103
	v_lshrrev_b32_e32 v99, 3, v76
	v_add3_u32 v174, s8, v80, v82
	v_and_b32_e32 v80, 0xffffffc0, v76
	v_ashrrev_i32_e32 v76, 7, v76
	s_and_b32 s39, s28, 0xc00
	v_lshlrev_b32_e32 v82, 3, v96
	v_readlane_b32 s9, v252, 37
	v_lshlrev_b32_e32 v86, 4, v76
	s_add_u32 s28, s39, s42
	v_add3_u32 v80, s9, v80, v82
	v_or_b32_e32 v82, v86, v93
	s_addc_u32 s29, 0, s45
	v_mul_lo_u32 v99, v99, s10
	v_mul_lo_u32 v87, v82, s7
	v_lshl_add_u64 v[84:85], s[28:29], 0, v[84:85]
	s_lshl_b64 s[28:29], s[30:31], 1
	v_lshlrev_b32_e32 v100, 1, v72
	v_add3_u32 v141, s6, v99, v91
	v_mul_lo_u32 v99, v77, s7
	v_add_u32_e32 v91, 16, v87
	v_lshlrev_b32_e32 v92, 4, v96
	v_lshlrev_b32_e32 v87, 1, v0
	v_lshlrev_b32_e32 v0, 4, v0
	s_add_u32 s30, s56, s42
	v_add3_u32 v168, 16, v100, v99
	v_and_b32_e32 v99, 2, v87
	v_or_b32_e32 v98, v98, v86
	v_and_or_b32 v0, v0, 16, v93
	v_mov_b32_e32 v87, s9
	v_mul_lo_u32 v82, v82, s10
	v_readlane_b32 s20, v252, 38
	v_add_u32_e32 v102, s8, v92
	v_lshl_add_u64 v[84:85], v[88:89], 1, v[84:85]
	s_addc_u32 s31, 0, s45
	v_mad_u32_u24 v101, v0, s7, v87
	v_add3_u32 v175, s20, v82, v92
	v_mad_u32_u24 v176, v0, s10, v102
	v_or_b32_e32 v0, v97, v93
	v_lshl_or_b32 v82, v99, 4, v93
	v_or_b32_e32 v107, 1, v98
	v_or_b32_e32 v108, 2, v98
	v_or_b32_e32 v109, 3, v98
	v_lshl_add_u64 v[134:135], v[84:85], 0, s[28:29]
	v_mov_b64_e32 v[84:85], s[30:31]
	v_add_u32_e32 v103, s6, v92
	v_cmp_le_i32_e64 s[6:7], v99, v76
	v_mul_u32_u24_e32 v105, 0x210, v82
	v_mul_lo_u32 v106, v98, s10
	v_cmp_ge_i32_e64 s[8:9], v99, v76
	v_or_b32_e32 v76, 16, v82
	v_mul_lo_u32 v99, v0, s10
	v_lshl_add_u32 v111, v82, 1, s20
	v_cmp_gt_i32_e64 s[10:11], v82, v98
	v_cmp_gt_i32_e64 s[12:13], v82, v107
	v_cmp_gt_i32_e64 s[14:15], v82, v108
	v_cmp_gt_i32_e64 s[16:17], v82, v109
	v_mad_i64_i32 v[82:83], s[30:31], v83, s51, v[84:85]
	v_lshl_add_u64 v[142:143], v[78:79], 1, v[82:83]
	v_mad_i64_i32 v[78:79], s[30:31], v81, s51, v[84:85]
	v_lshl_add_u64 v[144:145], v[74:75], 1, v[78:79]
	v_mad_i64_i32 v[74:75], s[30:31], v77, s51, v[84:85]
	v_ashrrev_i32_e32 v87, 31, v86
	v_lshl_add_u64 v[146:147], v[72:73], 1, v[74:75]
	v_mad_i64_i32 v[72:73], s[30:31], v90, s51, v[84:85]
	v_lshlrev_b32_e32 v0, 1, v76
	v_lshl_add_u64 v[148:149], v[70:71], 1, v[72:73]
	v_lshl_or_b32 v70, v96, 14, s34
	v_mov_b32_e32 v71, s35
	v_lshlrev_b64 v[72:73], 12, v[86:87]
	v_add3_u32 v177, s20, v106, v0
	v_lshl_add_u64 v[70:71], v[70:71], 0, v[72:73]
	v_and_b32_e32 v0, 32, v97
	v_or3_b32 v70, v70, s39, v0
	v_add_u32_e32 v100, 16, v92
	v_mul_u32_u24_e32 v104, 0x210, v93
	v_mul_u32_u24_e32 v110, 0x90, v93
	v_lshl_add_u64 v[70:71], v[70:71], 0, s[28:29]
	v_lshlrev_b32_e32 v0, 1, v93
	v_mov_b32_e32 v152, 0
	v_cmp_gt_i32_e64 s[18:19], v76, v98
	v_cmp_gt_i32_e64 s[20:21], v76, v107
	v_add_u32_e32 v178, 0x90, v177
	v_cmp_gt_i32_e64 s[22:23], v76, v108
	v_add_u32_e32 v179, 0x120, v177
	v_cmp_gt_i32_e64 s[24:25], v76, v109
	v_add_u32_e32 v180, 0x1b0, v177
	v_lshl_add_u64 v[132:133], s[54:55], 0, v[94:95]
	v_lshl_add_u64 v[150:151], v[70:71], 0, v[0:1]
	s_mov_b32 s34, 0
	v_add_u32_e32 v0, v80, v104
	v_add_u32_e32 v181, v91, v92
	v_add_u32_e32 v182, v111, v106
	v_add_u32_e32 v183, v101, v92
	v_add_u32_e32 v184, v103, v99
	v_add_u32_e32 v185, v102, v110
	v_add_u32_e32 v186, v100, v105
	v_mov_b32_e32 v153, v152
	v_mov_b32_e32 v154, v152
	v_mov_b32_e32 v155, v152
	v_mov_b32_e32 v156, v152
	v_mov_b32_e32 v157, v152
	v_mov_b32_e32 v158, v152
	v_mov_b32_e32 v159, v152
	v_mov_b32_e32 v160, v152
	v_mov_b32_e32 v161, v152
	v_mov_b32_e32 v162, v152
	v_mov_b32_e32 v163, v152
	v_mov_b32_e32 v164, v152
	v_mov_b32_e32 v165, v152
	v_mov_b32_e32 v166, v152
	v_mov_b32_e32 v167, v152
	v_readfirstlane_b32 s98, v139
	s_lshr_b32 s98, s98, 6
	s_cmp_lt_u32 s98, 4
	s_cbranch_scc1 .Lscan_noprio_g
	s_setprio 1
; template <int DK> ...
;     ...
;     bf16x8 qf[DK / 32];
;     {
;       const int ti = w >> 1;
; #pragma unroll
;       for (int ks = 0; ks < DK / 32; ++ks) qf[ks] = *(const bf16x8*)(Qt + (ti * 16 + fr) * PQ + ks * 32 + fq * 8);
; #pragma unroll
;       for (int x = 0; x < 2; ++x) {
;         const int tj = (w & 1) * 2 + x;
;         f32x4 a = {0.f, 0.f, 0.f, 0.f};
;         if (tj <= ti) {
; #pragma unroll
;           for (int ks = 0; ks < DK / 32; ++ks) {
;             bf16x8 fb = *(const bf16x8*)(Kt + (tj * 16 + fr) * PQ + ks * 32 + fq * 8);
;             a = __builtin_amdgcn_mfma_f32_16x16x32_bf16(qf[ks], fb, a, 0, 0, 0);
;           }
;         }
; #pragma unroll
;         for (int r = 0; r < 4; ++r) {
;           int i = ti * 16 + fq * 4 + r, j = tj * 16 + fr;
;           Pm[i * 72 + j] = f2bf(j <= i ? a[r] : 0.f);
;         }
;       }
;     }
;     RAWSYNC;
;     {
;       const int ti = w >> 1, tv = w & 1;
;       f32x4 a = {0.f, 0.f, 0.f, 0.f};
; #pragma unroll
;       for (int ks = 0; ks < DK / 32; ++ks) {
;         bf16x8 fb = *(const bf16x8*)(ST + (tv * 16 + fr) * PQ + ks * 32 + fq * 8);
;         a = __builtin_amdgcn_mfma_f32_16x16x32_bf16(qf[ks], fb, a, 0, 0, 0);
;       }
; #pragma unroll
;       for (int ks = 0; ks < 2; ++ks) {
;         bf16x8 fa = *(const bf16x8*)(Pm + (ti * 16 + fr) * 72 + ks * 32 + fq * 8);
;         bf16x8 fb = *(const bf16x8*)(VT + (tv * 16 + fr) * 72 + ks * 32 + fq * 8);
;         a = __builtin_amdgcn_mfma_f32_16x16x32_bf16(fa, fb, a, 0, 0, 0);
;       }
; #pragma unroll
;       for (int r = 0; r < 4; ++r) og[(row + ti * 16 + fq * 4 + r) * 2048 + tv * 16 + fr] = f2bf(a[r]);
;     }
; #pragma unroll
;     for (int a = 0; a < NA; ++a) {
;       const int dt = w * NA + a;
; #pragma unroll
;       for (int tv = 0; tv < 2; ++tv) {
;         f32x4 u = {0.f, 0.f, 0.f, 0.f};
; #pragma unroll
;         for (int ks = 0; ks < 2; ++ks) {
;           bf16x8 fa = *(const bf16x8*)(KtT + (dt * 16 + fr) * 72 + ks * 32 + fq * 8);
;           bf16x8 fb = *(const bf16x8*)(VT + (tv * 16 + fr) * 72 + ks * 32 + fq * 8);
;           u = __builtin_amdgcn_mfma_f32_16x16x32_bf16(fa, fb, u, 0, 0, 0);
;         }
;         S[a][tv][0] = e4[a].x * l4[a].x * S[a][tv][0] + l4[a].x * u[0];
;         S[a][tv][1] = e4[a].y * l4[a].y * S[a][tv][1] + l4[a].y * u[1];
;         S[a][tv][2] = e4[a].z * l4[a].z * S[a][tv][2] + l4[a].z * u[2];
.Lscan_noprio_g:
	s_branch .LBB0_252
.LBB0_251:
	s_or_b64 exec, exec, s[28:29]
	s_nop 5
	v_cvt_pk_bf16_f32 v118, v118, s0
	v_cndmask_b32_e64 v118, v118, 0, s[18:19]
	ds_write_b16 v177, v118
	v_cvt_pk_bf16_f32 v118, v119, s0
	v_cndmask_b32_e64 v118, v118, 0, s[20:21]
	ds_write_b16 v178, v118
	v_cvt_pk_bf16_f32 v118, v120, s0
	v_cndmask_b32_e64 v118, v118, 0, s[22:23]
	ds_write_b16 v179, v118
	v_cvt_pk_bf16_f32 v118, v121, s0
	v_cndmask_b32_e64 v118, v118, 0, s[24:25]
	ds_write_b16 v180, v118
	s_waitcnt lgkmcnt(0)
	s_barrier
	ds_read_b128 v[216:219], v183
	ds_read_b128 v[220:223], v183 offset:64
	ds_read_b128 v[224:227], v183 offset:128
	ds_read_b128 v[228:231], v183 offset:192
	ds_read_b128 v[232:235], v183 offset:256
	ds_read_b128 v[236:239], v183 offset:320
	ds_read_b128 v[240:243], v183 offset:384
	ds_read_b128 v[244:247], v183 offset:448
	ds_read_b128 v[248:251], v175
	ds_read_b128 v[212:215], v176
	ds_read_b128 v[118:121], v175 offset:64
	s_movk_i32 s28, 0x1000
	s_add_i32 s34, s34, 1
	s_movk_i32 s86, 0x1000
	v_lshl_add_u64 v[134:135], v[134:135], 0, s[70:71]
	v_lshl_add_u64 v[142:143], v[142:143], 0, s[70:71]
	v_lshl_add_u64 v[144:145], v[144:145], 0, s[70:71]
	v_lshl_add_u64 v[146:147], v[146:147], 0, s[70:71]
	v_lshl_add_u64 v[148:149], v[148:149], 0, s[70:71]
	s_cmpk_lg_i32 s34, 0x80
	s_waitcnt lgkmcnt(10)
	v_mfma_f32_16x16x32_bf16 v[114:117], v[114:117], v[216:219], 0
	s_waitcnt lgkmcnt(9)
	v_mfma_f32_16x16x32_bf16 v[110:113], v[110:113], v[220:223], v[114:117]
	s_waitcnt lgkmcnt(8)
	v_mfma_f32_16x16x32_bf16 v[106:109], v[106:109], v[224:227], v[110:113]
	s_waitcnt lgkmcnt(7)
	v_mfma_f32_16x16x32_bf16 v[102:105], v[102:105], v[228:231], v[106:109]
	s_waitcnt lgkmcnt(6)
	v_mfma_f32_16x16x32_bf16 v[98:101], v[98:101], v[232:235], v[102:105]
	s_waitcnt lgkmcnt(5)
	v_mfma_f32_16x16x32_bf16 v[94:97], v[94:97], v[236:239], v[98:101]
	s_waitcnt lgkmcnt(4)
	v_mfma_f32_16x16x32_bf16 v[90:93], v[90:93], v[240:243], v[94:97]
	s_waitcnt lgkmcnt(3)
	v_mfma_f32_16x16x32_bf16 v[86:89], v[86:89], v[244:247], v[90:93]
	s_nop 2
	ds_read_b128 v[94:97], v176 offset:64
	v_pk_mul_f32 v[106:107], v[62:63], v[66:67]
	v_pk_mul_f32 v[108:109], v[64:65], v[68:69]
	s_waitcnt lgkmcnt(2)
	v_mfma_f32_16x16x32_bf16 v[86:89], v[248:251], v[212:215], v[86:89]
	s_waitcnt lgkmcnt(0)
	v_mfma_f32_16x16x32_bf16 v[86:89], v[118:121], v[94:97], v[86:89]
	v_lshl_add_u64 v[90:91], s[66:67], 0, v[150:151]
	s_nop 6
	v_cvt_pk_bf16_f32 v86, v86, s0
	global_store_short v[90:91], v86, off
	v_add_co_u32_e32 v86, vcc, s28, v90
	v_cvt_pk_bf16_f32 v92, v87, s0
	s_nop 0
	v_addc_co_u32_e32 v87, vcc, 0, v91, vcc
	global_store_short v[86:87], v92, off
	v_add_co_u32_e32 v86, vcc, s43, v90
	v_cvt_pk_bf16_f32 v88, v88, s0
	s_nop 0
	v_addc_co_u32_e32 v87, vcc, 0, v91, vcc
	global_store_short v[86:87], v88, off
	v_add_co_u32_e32 v86, vcc, s69, v90
	v_cvt_pk_bf16_f32 v88, v89, s0
	s_nop 0
	v_addc_co_u32_e32 v87, vcc, 0, v91, vcc
	global_store_short v[86:87], v88, off
	ds_read_b128 v[216:219], v184
	ds_read_b128 v[224:227], v185
	ds_read_b128 v[220:223], v184 offset:64
	ds_read_b128 v[228:231], v185 offset:64
	ds_read_b128 v[232:235], v185 offset:2304
	ds_read_b128 v[236:239], v185 offset:2368
	ds_read_b128 v[240:243], v184 offset:2304
	ds_read_b128 v[244:247], v184 offset:2368
	s_mov_b64 s[28:29], 0x40000
	v_lshl_add_u64 v[150:151], v[150:151], 0, s[28:29]
	s_waitcnt lgkmcnt(6)
	v_mfma_f32_16x16x32_bf16 v[90:93], v[216:219], v[224:227], 0
	s_waitcnt lgkmcnt(4)
	v_mfma_f32_16x16x32_bf16 v[90:93], v[220:223], v[228:231], v[90:93]
	s_waitcnt lgkmcnt(3)
	v_mfma_f32_16x16x32_bf16 v[66:69], v[216:219], v[232:235], 0
	s_waitcnt lgkmcnt(2)
	v_mfma_f32_16x16x32_bf16 v[66:69], v[220:223], v[236:239], v[66:69]
	s_nop 7
	v_pk_mul_f32 v[92:93], v[64:65], v[92:93]
	v_pk_mul_f32 v[90:91], v[62:63], v[90:91]
	v_pk_fma_f32 v[154:155], v[108:109], v[154:155], v[92:93]
	v_pk_fma_f32 v[152:153], v[106:107], v[152:153], v[90:91]
	v_mul_f32_e64 v94, v54, v58
	v_mul_f32_e64 v95, v55, v59
	v_pk_mul_f32 v[96:97], v[56:57], v[60:61]
	s_nop 3
	v_pk_mul_f32 v[64:65], v[64:65], v[68:69]
	v_pk_mul_f32 v[62:63], v[62:63], v[66:67]
	v_pk_fma_f32 v[158:159], v[108:109], v[158:159], v[64:65]
	v_pk_fma_f32 v[156:157], v[106:107], v[156:157], v[62:63]
	s_waitcnt lgkmcnt(1)
	v_mfma_f32_16x16x32_bf16 v[62:65], v[240:243], v[224:227], 0
	v_mfma_f32_16x16x32_bf16 v[58:61], v[240:243], v[232:235], 0
	s_waitcnt lgkmcnt(0)
	v_mfma_f32_16x16x32_bf16 v[62:65], v[244:247], v[228:231], v[62:65]
	v_mfma_f32_16x16x32_bf16 v[58:61], v[244:247], v[236:239], v[58:61]
	s_waitcnt vmcnt(0)
	v_mov_b64_e32 v[66:67], v[70:71]
	s_nop 4
	v_pk_mul_f32 v[64:65], v[56:57], v[64:65]
	v_pk_mul_f32 v[62:63], v[54:55], v[62:63]
	v_pk_fma_f32 v[162:163], v[96:97], v[162:163], v[64:65]
	v_pk_fma_f32 v[160:161], v[94:95], v[160:161], v[62:63]
	v_pk_mul_f32 v[56:57], v[56:57], v[60:61]
	v_pk_mul_f32 v[54:55], v[54:55], v[58:59]
	v_pk_fma_f32 v[166:167], v[96:97], v[166:167], v[56:57]
	v_pk_fma_f32 v[164:165], v[94:95], v[164:165], v[54:55]
	v_mov_b64_e32 v[54:55], v[82:83]
	v_mov_b64_e32 v[58:59], v[78:79]
	v_mov_b64_e32 v[56:57], v[84:85]
	v_mov_b64_e32 v[60:61], v[80:81]
	v_mov_b64_e32 v[62:63], v[74:75]
	v_mov_b64_e32 v[64:65], v[76:77]
	v_mov_b64_e32 v[68:69], v[72:73]
	s_cbranch_scc0 .LBB0_224
